# prompt band attention steps get the same: V fragment reads hoisted behind the bias lookups, permlane running max, bpermute waits removed
# speedup vs baseline: 1.0221x; 1.0043x over previous
.LBB0_872:
	v_add_u32_e32 v16, v51, v80
	ds_read_b128 v[52:55], v16
	ds_read_b128 v[56:59], v16 offset:64
	ds_read_b128 v[60:63], v16 offset:2560
	ds_read_b128 v[86:89], v16 offset:2624
	ds_read_b128 v[90:93], v16 offset:5120
	ds_read_b128 v[94:97], v16 offset:5184
	s_waitcnt lgkmcnt(5)
	v_mfma_f32_16x16x32_bf16 v[52:55], v[52:55], v[0:3], 0
	s_waitcnt lgkmcnt(3)
	v_mfma_f32_16x16x32_bf16 v[60:63], v[60:63], v[0:3], 0
	v_mfma_f32_16x16x32_bf16 v[52:55], v[56:59], v[4:7], v[52:55]
	ds_read_b128 v[56:59], v16 offset:7680
	ds_read_b128 v[98:101], v16 offset:7744
	s_waitcnt lgkmcnt(4)
	v_mfma_f32_16x16x32_bf16 v[86:89], v[86:89], v[4:7], v[60:63]
	s_waitcnt lgkmcnt(3)
	v_mfma_f32_16x16x32_bf16 v[60:63], v[90:93], v[0:3], 0
	s_waitcnt lgkmcnt(2)
	v_mfma_f32_16x16x32_bf16 v[90:93], v[94:97], v[4:7], v[60:63]
	s_cmp_lt_i32 s18, s19
	s_waitcnt lgkmcnt(1)
	v_mfma_f32_16x16x32_bf16 v[56:59], v[56:59], v[0:3], 0
	s_waitcnt lgkmcnt(0)
	v_mfma_f32_16x16x32_bf16 v[94:97], v[98:101], v[4:7], v[56:59]
	v_lshlrev_b32_e32 v112, 2, v82
	v_add_u32_e32 v112, 0x5400, v112
	ds_read2_b32 v[18:19], v112 offset0:51 offset1:50
	ds_read2_b32 v[56:57], v112 offset0:49 offset1:48
	ds_read2_b32 v[60:61], v112 offset0:35 offset1:34
	ds_read2_b32 v[58:59], v112 offset0:33 offset1:32
	ds_read2_b32 v[98:99], v112 offset0:19 offset1:18
	ds_read2_b32 v[100:101], v112 offset0:17 offset1:16
	ds_read2_b32 v[102:103], v112 offset0:3 offset1:2
	ds_read2_b32 v[104:105], v112 offset0:1 offset1:0
	s_waitcnt lgkmcnt(6)
	v_pk_add_f32 v[62:63], v[54:55], v[56:57]
	v_pk_add_f32 v[64:65], v[52:53], v[18:19]
	s_waitcnt lgkmcnt(4)
	v_pk_add_f32 v[58:59], v[88:89], v[58:59]
	v_pk_add_f32 v[60:61], v[86:87], v[60:61]
	s_waitcnt lgkmcnt(2)
	v_pk_add_f32 v[52:53], v[92:93], v[100:101]
	v_pk_add_f32 v[54:55], v[90:91], v[98:99]
	s_waitcnt lgkmcnt(0)
	ds_read_b64_tr_b16 v[140:141], v67
	ds_read_b64_tr_b16 v[144:145], v67 offset:32
	ds_read_b64_tr_b16 v[148:149], v67 offset:64
	ds_read_b64_tr_b16 v[152:153], v67 offset:96
	ds_read_b64_tr_b16 v[142:143], v67 offset:2560
	ds_read_b64_tr_b16 v[146:147], v67 offset:2592
	ds_read_b64_tr_b16 v[150:151], v67 offset:2624
	ds_read_b64_tr_b16 v[154:155], v67 offset:2656
	ds_read_b64_tr_b16 v[156:157], v81
	ds_read_b64_tr_b16 v[160:161], v81 offset:32
	ds_read_b64_tr_b16 v[164:165], v81 offset:64
	ds_read_b64_tr_b16 v[168:169], v81 offset:96
	ds_read_b64_tr_b16 v[158:159], v81 offset:2560
	ds_read_b64_tr_b16 v[162:163], v81 offset:2592
	ds_read_b64_tr_b16 v[166:167], v81 offset:2624
	ds_read_b64_tr_b16 v[170:171], v81 offset:2656
	v_pk_add_f32 v[18:19], v[96:97], v[104:105]
	v_pk_add_f32 v[56:57], v[94:95], v[102:103]
	s_cbranch_scc1 .LBB0_874
	v_add_u32_e32 v16, s18, v66
	v_add_u32_e32 v87, 3, v16
	v_add_u32_e32 v88, 16, v16
	v_add_u32_e32 v86, 2, v16
	v_cmp_gt_i32_e64 s[4:5], s19, v87
	v_cmp_gt_i32_e64 s[6:7], s19, v88
	v_add_u32_e32 v85, 1, v16
	v_cmp_gt_i32_e64 s[2:3], s19, v86
	s_or_b64 s[4:5], s[6:7], s[4:5]
	v_cmp_gt_i32_e64 s[0:1], s19, v85
	s_or_b64 s[2:3], s[4:5], s[2:3]
	v_cmp_gt_i32_e32 vcc, s19, v16
	s_or_b64 s[0:1], s[2:3], s[0:1]
	v_add_u32_e32 v89, 17, v16
	s_or_b64 vcc, s[0:1], vcc
	v_add_u32_e32 v90, 18, v16
	v_cndmask_b32_e32 v64, v76, v64, vcc
	v_cmp_gt_i32_e32 vcc, s19, v89
	v_add_u32_e32 v91, 19, v16
	v_add_u32_e32 v92, 32, v16
	v_cndmask_b32_e32 v61, v76, v61, vcc
	v_cmp_gt_i32_e32 vcc, s19, v90
	v_cndmask_b32_e64 v65, v76, v65, s[0:1]
	v_cmp_gt_i32_e64 s[0:1], s19, v92
	v_cndmask_b32_e32 v58, v76, v58, vcc
	v_cmp_gt_i32_e32 vcc, s19, v91
	v_add_u32_e32 v93, 33, v16
	s_or_b64 vcc, s[0:1], vcc
	v_add_u32_e32 v94, 34, v16
	v_cndmask_b32_e32 v59, v76, v59, vcc
	v_cmp_gt_i32_e32 vcc, s19, v93
	v_add_u32_e32 v95, 35, v16
	v_add_u32_e32 v96, 48, v16
	v_cndmask_b32_e32 v55, v76, v55, vcc
	v_cmp_gt_i32_e32 vcc, s19, v94
	v_cndmask_b32_e64 v54, v76, v54, s[0:1]
	v_cmp_gt_i32_e64 s[0:1], s19, v96
	v_cndmask_b32_e32 v52, v76, v52, vcc
	v_cmp_gt_i32_e32 vcc, s19, v95
	v_add_u32_e32 v97, 49, v16
	s_or_b64 vcc, s[0:1], vcc
	v_add_u32_e32 v98, 50, v16
	v_cndmask_b32_e32 v53, v76, v53, vcc
	v_cmp_gt_i32_e32 vcc, s19, v97
	v_add_u32_e32 v99, 51, v16
	v_cndmask_b32_e64 v60, v76, v60, s[6:7]
	v_cndmask_b32_e32 v57, v76, v57, vcc
	v_cmp_gt_i32_e32 vcc, s19, v98
	v_cndmask_b32_e64 v63, v76, v63, s[4:5]
	v_cndmask_b32_e64 v62, v76, v62, s[2:3]
	v_cndmask_b32_e32 v18, v76, v18, vcc
	v_cmp_gt_i32_e32 vcc, s19, v99
	v_cndmask_b32_e64 v56, v76, v56, s[0:1]
	s_nop 0
	v_cndmask_b32_e32 v19, v76, v19, vcc
.LBB0_874:
	s_mov_b32 s0, 0xff800000
	v_max3_f32 v16, v64, s0, v65
	v_max3_f32 v16, v16, v62, v63
	v_max3_f32 v16, v16, v60, v61
	v_mbcnt_hi_u32_b32 v85, -1, v204
	v_max3_f32 v16, v16, v58, v59
	v_and_b32_e32 v87, 64, v85
	v_max3_f32 v16, v16, v54, v55
	v_xor_b32_e32 v86, 16, v85
	v_add_u32_e32 v87, 64, v87
	v_max3_f32 v16, v16, v52, v53
	v_cmp_lt_i32_e32 vcc, v86, v87
	v_max3_f32 v16, v16, v56, v57
	v_max3_f32 v16, v16, v18, v19
	v_cndmask_b32_e32 v86, v85, v86, vcc
	v_lshlrev_b32_e32 v86, 2, v86
	v_mov_b32_e32 v86, v16
	s_nop 1
	v_permlane16_swap_b32_e32 v86, v16
	v_max_f32_e32 v16, v16, v86
	v_xor_b32_e32 v86, 32, v85
	v_cmp_lt_i32_e32 vcc, v86, v87
	s_nop 1
	v_cndmask_b32_e32 v85, v85, v86, vcc
	v_lshlrev_b32_e32 v85, 2, v85
	v_mov_b32_e32 v85, v16
	s_nop 1
	v_permlane32_swap_b32_e32 v85, v16
	v_max3_f32 v92, v84, v16, v85
	v_cmp_neq_f32_e32 vcc, s0, v92
	s_nop 1
	v_cndmask_b32_e32 v16, 0, v92, vcc
	v_sub_f32_e32 v64, v64, v16
	v_exp_f32_e32 v64, v64
	v_sub_f32_e32 v65, v65, v16
	v_exp_f32_e32 v65, v65
	v_sub_f32_e32 v62, v62, v16
	v_exp_f32_e32 v62, v62
	v_sub_f32_e32 v63, v63, v16
	v_exp_f32_e32 v63, v63
	v_sub_f32_e32 v60, v60, v16
	v_add_f32_e32 v85, 0, v64
	v_exp_f32_e32 v60, v60
	v_sub_f32_e32 v61, v61, v16
	v_add_f32_e32 v85, v65, v85
	v_exp_f32_e32 v61, v61
	v_sub_f32_e32 v58, v58, v16
	v_add_f32_e32 v85, v62, v85
	v_exp_f32_e32 v58, v58
	v_sub_f32_e32 v59, v59, v16
	v_add_f32_e32 v85, v63, v85
	v_exp_f32_e32 v59, v59
	v_sub_f32_e32 v54, v54, v16
	v_add_f32_e32 v85, v60, v85
	v_exp_f32_e32 v93, v54
	v_sub_f32_e32 v55, v55, v16
	v_add_f32_e32 v85, v61, v85
	v_exp_f32_e32 v94, v55
	v_sub_f32_e32 v52, v52, v16
	v_add_f32_e32 v85, v58, v85
	v_exp_f32_e32 v95, v52
	v_sub_f32_e32 v53, v53, v16
	v_add_f32_e32 v85, v59, v85
	v_exp_f32_e32 v96, v53
	v_sub_f32_e32 v53, v56, v16
	v_add_f32_e32 v54, v93, v85
	v_exp_f32_e32 v97, v53
	v_sub_f32_e32 v53, v57, v16
	v_sub_f32_e32 v84, v84, v16
	v_add_f32_e32 v54, v94, v54
	v_exp_f32_e32 v98, v53
	v_sub_f32_e32 v18, v18, v16
	v_sub_f32_e32 v16, v19, v16
	v_add_f32_e32 v52, v95, v54
	v_exp_f32_e32 v18, v18
	v_exp_f32_e32 v19, v16
	v_exp_f32_e32 v16, v84
	v_add_f32_e32 v52, v96, v52
	v_add_f32_e32 v52, v97, v52
	v_add_f32_e32 v52, v98, v52
	v_add_f32_e32 v52, v18, v52
	v_pk_mul_f32 v[30:31], v[30:31], v[16:17] op_sel_hi:[1,0]
	v_pk_mul_f32 v[28:29], v[28:29], v[16:17] op_sel_hi:[1,0]
	v_pk_mul_f32 v[38:39], v[38:39], v[16:17] op_sel_hi:[1,0]
	v_pk_mul_f32 v[36:37], v[36:37], v[16:17] op_sel_hi:[1,0]
	v_pk_mul_f32 v[42:43], v[42:43], v[16:17] op_sel_hi:[1,0]
	v_pk_mul_f32 v[40:41], v[40:41], v[16:17] op_sel_hi:[1,0]
	v_pk_mul_f32 v[34:35], v[34:35], v[16:17] op_sel_hi:[1,0]
	v_pk_mul_f32 v[32:33], v[32:33], v[16:17] op_sel_hi:[1,0]
	v_add_f32_e32 v99, v19, v52
	v_cvt_pk_bf16_f32 v52, v64, v65
	v_cvt_pk_bf16_f32 v53, v62, v63
	v_cvt_pk_bf16_f32 v54, v60, v61
	v_cvt_pk_bf16_f32 v55, v58, v59
	s_waitcnt lgkmcnt(0)
	v_fmac_f32_e32 v99, v83, v16
	v_mfma_f32_16x16x32_bf16 v[28:31], v[140:143], v[52:55], v[28:31]
	v_mov_b32_e32 v83, v99
	v_mfma_f32_16x16x32_bf16 v[36:39], v[144:147], v[52:55], v[36:39]
	v_mfma_f32_16x16x32_bf16 v[40:43], v[148:151], v[52:55], v[40:43]
	v_mfma_f32_16x16x32_bf16 v[32:35], v[152:155], v[52:55], v[32:35]
	v_cvt_pk_bf16_f32 v52, v93, v94
	v_cvt_pk_bf16_f32 v53, v95, v96
	v_cvt_pk_bf16_f32 v54, v97, v98
	v_cvt_pk_bf16_f32 v55, v18, v19
	s_waitcnt lgkmcnt(0)
	s_nop 0
	v_mfma_f32_16x16x32_bf16 v[28:31], v[156:159], v[52:55], v[28:31]
	v_mfma_f32_16x16x32_bf16 v[36:39], v[160:163], v[52:55], v[36:39]
	v_mov_b32_e32 v84, v92
	v_mfma_f32_16x16x32_bf16 v[40:43], v[164:167], v[52:55], v[40:43]
	v_mfma_f32_16x16x32_bf16 v[32:35], v[168:171], v[52:55], v[32:35]
	s_or_b64 exec, exec, s[12:13]
	s_add_i32 s0, s21, 1
	s_cmp_ge_i32 s0, s16
	s_cbranch_scc1 .LBB0_871

.LBB0_877:
	v_cmp_lt_i32_e32 vcc, s0, v68
	v_cmp_ge_i32_e64 s[0:1], s0, v69
	s_or_b64 s[0:1], vcc, s[0:1]
	s_nor_b64 s[0:1], s[8:9], s[0:1]
	s_and_saveexec_b64 s[12:13], s[0:1]
	s_cbranch_execz .LBB0_881
	v_add_u32_e32 v16, v51, v80
	ds_read_b128 v[52:55], v16
	ds_read_b128 v[56:59], v16 offset:64
	ds_read_b128 v[60:63], v16 offset:2560
	ds_read_b128 v[86:89], v16 offset:2624
	ds_read_b128 v[90:93], v16 offset:5120
	s_waitcnt lgkmcnt(4)
	v_mfma_f32_16x16x32_bf16 v[52:55], v[52:55], v[0:3], 0
	s_waitcnt lgkmcnt(2)
	v_mfma_f32_16x16x32_bf16 v[60:63], v[60:63], v[0:3], 0
	v_mfma_f32_16x16x32_bf16 v[52:55], v[56:59], v[4:7], v[52:55]
	ds_read_b128 v[56:59], v16 offset:5184
	ds_read_b128 v[94:97], v16 offset:7680
	ds_read_b128 v[98:101], v16 offset:7744
	s_waitcnt lgkmcnt(4)
	v_mfma_f32_16x16x32_bf16 v[86:89], v[86:89], v[4:7], v[60:63]
	s_waitcnt lgkmcnt(3)
	v_mfma_f32_16x16x32_bf16 v[60:63], v[90:93], v[0:3], 0
	s_waitcnt lgkmcnt(2)
	v_mfma_f32_16x16x32_bf16 v[90:93], v[56:59], v[4:7], v[60:63]
	s_add_i32 s0, s18, 64
	s_waitcnt lgkmcnt(1)
	v_mfma_f32_16x16x32_bf16 v[56:59], v[94:97], v[0:3], 0
	s_waitcnt lgkmcnt(0)
	v_mfma_f32_16x16x32_bf16 v[94:97], v[98:101], v[4:7], v[56:59]
	v_lshlrev_b32_e32 v112, 2, v82
	v_add_u32_e32 v112, 0x5300, v112
	ds_read2_b32 v[18:19], v112 offset0:51 offset1:50
	ds_read2_b32 v[56:57], v112 offset0:49 offset1:48
	ds_read2_b32 v[60:61], v112 offset0:35 offset1:34
	ds_read2_b32 v[58:59], v112 offset0:33 offset1:32
	ds_read2_b32 v[98:99], v112 offset0:19 offset1:18
	ds_read2_b32 v[100:101], v112 offset0:17 offset1:16
	ds_read2_b32 v[102:103], v112 offset0:3 offset1:2
	ds_read2_b32 v[104:105], v112 offset0:1 offset1:0
	s_waitcnt lgkmcnt(6)
	v_pk_add_f32 v[62:63], v[54:55], v[56:57]
	v_pk_add_f32 v[64:65], v[52:53], v[18:19]
	s_waitcnt lgkmcnt(4)
	v_pk_add_f32 v[58:59], v[88:89], v[58:59]
	v_pk_add_f32 v[60:61], v[86:87], v[60:61]
	s_waitcnt lgkmcnt(2)
	v_pk_add_f32 v[52:53], v[92:93], v[100:101]
	v_pk_add_f32 v[54:55], v[90:91], v[98:99]
	s_waitcnt lgkmcnt(0)
	ds_read_b64_tr_b16 v[140:141], v67
	ds_read_b64_tr_b16 v[144:145], v67 offset:32
	ds_read_b64_tr_b16 v[148:149], v67 offset:64
	ds_read_b64_tr_b16 v[152:153], v67 offset:96
	ds_read_b64_tr_b16 v[142:143], v67 offset:2560
	ds_read_b64_tr_b16 v[146:147], v67 offset:2592
	ds_read_b64_tr_b16 v[150:151], v67 offset:2624
	ds_read_b64_tr_b16 v[154:155], v67 offset:2656
	ds_read_b64_tr_b16 v[156:157], v81
	ds_read_b64_tr_b16 v[160:161], v81 offset:32
	ds_read_b64_tr_b16 v[164:165], v81 offset:64
	ds_read_b64_tr_b16 v[168:169], v81 offset:96
	ds_read_b64_tr_b16 v[158:159], v81 offset:2560
	ds_read_b64_tr_b16 v[162:163], v81 offset:2592
	ds_read_b64_tr_b16 v[166:167], v81 offset:2624
	ds_read_b64_tr_b16 v[170:171], v81 offset:2656
	v_pk_add_f32 v[18:19], v[96:97], v[104:105]
	s_cmp_lt_i32 s0, s19
	v_pk_add_f32 v[56:57], v[94:95], v[102:103]
	s_cbranch_scc1 .LBB0_880
	v_add_u32_e32 v16, s18, v66
	v_add_u32_e32 v88, 0x43, v16
	v_add_u32_e32 v89, 0x50, v16
	v_add_u32_e32 v87, 0x42, v16
	v_cmp_gt_i32_e64 s[4:5], s19, v88
	v_cmp_gt_i32_e64 s[6:7], s19, v89
	v_add_u32_e32 v86, 0x41, v16
	v_cmp_gt_i32_e64 s[2:3], s19, v87
	s_or_b64 s[4:5], s[6:7], s[4:5]
	v_add_u32_e32 v85, 64, v16
	v_cmp_gt_i32_e64 s[0:1], s19, v86
	s_or_b64 s[2:3], s[4:5], s[2:3]
	v_cmp_gt_i32_e32 vcc, s19, v85
	s_or_b64 s[0:1], s[2:3], s[0:1]
	v_add_u32_e32 v90, 0x51, v16
	s_or_b64 vcc, s[0:1], vcc
	v_add_u32_e32 v91, 0x52, v16
	v_cndmask_b32_e32 v64, v76, v64, vcc
	v_cmp_gt_i32_e32 vcc, s19, v90
	v_add_u32_e32 v92, 0x53, v16
	v_add_u32_e32 v93, 0x60, v16
	v_cndmask_b32_e32 v61, v76, v61, vcc
	v_cmp_gt_i32_e32 vcc, s19, v91
	v_cndmask_b32_e64 v65, v76, v65, s[0:1]
	v_cmp_gt_i32_e64 s[0:1], s19, v93
	v_cndmask_b32_e32 v58, v76, v58, vcc
	v_cmp_gt_i32_e32 vcc, s19, v92
	v_add_u32_e32 v94, 0x61, v16
	s_or_b64 vcc, s[0:1], vcc
	v_add_u32_e32 v95, 0x62, v16
	v_cndmask_b32_e32 v59, v76, v59, vcc
	v_cmp_gt_i32_e32 vcc, s19, v94
	v_add_u32_e32 v96, 0x63, v16
	v_add_u32_e32 v97, 0x70, v16
	v_cndmask_b32_e32 v55, v76, v55, vcc
	v_cmp_gt_i32_e32 vcc, s19, v95
	v_cndmask_b32_e64 v54, v76, v54, s[0:1]
	v_cmp_gt_i32_e64 s[0:1], s19, v97
	v_cndmask_b32_e32 v52, v76, v52, vcc
	v_cmp_gt_i32_e32 vcc, s19, v96
	v_add_u32_e32 v98, 0x71, v16
	s_or_b64 vcc, s[0:1], vcc
	v_add_u32_e32 v99, 0x72, v16
	v_cndmask_b32_e32 v53, v76, v53, vcc
	v_cmp_gt_i32_e32 vcc, s19, v98
	v_add_u32_e32 v16, 0x73, v16
	v_cndmask_b32_e64 v60, v76, v60, s[6:7]
	v_cndmask_b32_e32 v57, v76, v57, vcc
	v_cmp_gt_i32_e32 vcc, s19, v99
	v_cndmask_b32_e64 v63, v76, v63, s[4:5]
	v_cndmask_b32_e64 v62, v76, v62, s[2:3]
	v_cndmask_b32_e32 v18, v76, v18, vcc
	v_cmp_gt_i32_e32 vcc, s19, v16
	v_cndmask_b32_e64 v56, v76, v56, s[0:1]
	s_nop 0
	v_cndmask_b32_e32 v19, v76, v19, vcc
.LBB0_880:
	s_mov_b32 s0, 0xff800000
	v_max3_f32 v16, v64, s0, v65
	v_max3_f32 v16, v16, v62, v63
	v_max3_f32 v16, v16, v60, v61
	v_mbcnt_hi_u32_b32 v85, -1, v204
	v_max3_f32 v16, v16, v58, v59
	v_and_b32_e32 v87, 64, v85
	v_max3_f32 v16, v16, v54, v55
	v_xor_b32_e32 v86, 16, v85
	v_add_u32_e32 v87, 64, v87
	v_max3_f32 v16, v16, v52, v53
	v_cmp_lt_i32_e32 vcc, v86, v87
	v_max3_f32 v16, v16, v56, v57
	v_max3_f32 v16, v16, v18, v19
	v_cndmask_b32_e32 v86, v85, v86, vcc
	v_lshlrev_b32_e32 v86, 2, v86
	v_mov_b32_e32 v86, v16
	s_nop 1
	v_permlane16_swap_b32_e32 v86, v16
	v_max_f32_e32 v16, v16, v86
	v_xor_b32_e32 v86, 32, v85
	v_cmp_lt_i32_e32 vcc, v86, v87
	s_nop 1
	v_cndmask_b32_e32 v85, v85, v86, vcc
	v_lshlrev_b32_e32 v85, 2, v85
	v_mov_b32_e32 v85, v16
	s_nop 1
	v_permlane32_swap_b32_e32 v85, v16
	v_max3_f32 v92, v84, v16, v85
	v_cmp_neq_f32_e32 vcc, s0, v92
	s_nop 1
	v_cndmask_b32_e32 v16, 0, v92, vcc
	v_sub_f32_e32 v64, v64, v16
	v_exp_f32_e32 v64, v64
	v_sub_f32_e32 v65, v65, v16
	v_exp_f32_e32 v65, v65
	v_sub_f32_e32 v62, v62, v16
	v_exp_f32_e32 v62, v62
	v_sub_f32_e32 v63, v63, v16
	v_exp_f32_e32 v63, v63
	v_sub_f32_e32 v60, v60, v16
	v_add_f32_e32 v85, 0, v64
	v_exp_f32_e32 v60, v60
	v_sub_f32_e32 v61, v61, v16
	v_add_f32_e32 v85, v65, v85
	v_exp_f32_e32 v61, v61
	v_sub_f32_e32 v58, v58, v16
	v_add_f32_e32 v85, v62, v85
	v_exp_f32_e32 v58, v58
	v_sub_f32_e32 v59, v59, v16
	v_add_f32_e32 v85, v63, v85
	v_exp_f32_e32 v59, v59
	v_sub_f32_e32 v54, v54, v16
	v_add_f32_e32 v85, v60, v85
	v_exp_f32_e32 v93, v54
	v_sub_f32_e32 v55, v55, v16
	v_add_f32_e32 v85, v61, v85
	v_exp_f32_e32 v94, v55
	v_sub_f32_e32 v52, v52, v16
	v_add_f32_e32 v85, v58, v85
	v_exp_f32_e32 v95, v52
	v_sub_f32_e32 v53, v53, v16
	v_add_f32_e32 v85, v59, v85
	v_exp_f32_e32 v96, v53
	v_sub_f32_e32 v53, v56, v16
	v_add_f32_e32 v54, v93, v85
	v_exp_f32_e32 v97, v53
	v_sub_f32_e32 v53, v57, v16
	v_sub_f32_e32 v84, v84, v16
	v_add_f32_e32 v54, v94, v54
	v_exp_f32_e32 v98, v53
	v_sub_f32_e32 v18, v18, v16
	v_sub_f32_e32 v16, v19, v16
	v_add_f32_e32 v52, v95, v54
	v_exp_f32_e32 v18, v18
	v_exp_f32_e32 v19, v16
	v_exp_f32_e32 v16, v84
	v_add_f32_e32 v52, v96, v52
	v_add_f32_e32 v52, v97, v52
	v_add_f32_e32 v52, v98, v52
	v_add_f32_e32 v52, v18, v52
	v_pk_mul_f32 v[30:31], v[30:31], v[16:17] op_sel_hi:[1,0]
	v_pk_mul_f32 v[28:29], v[28:29], v[16:17] op_sel_hi:[1,0]
	v_pk_mul_f32 v[38:39], v[38:39], v[16:17] op_sel_hi:[1,0]
	v_pk_mul_f32 v[36:37], v[36:37], v[16:17] op_sel_hi:[1,0]
	v_pk_mul_f32 v[42:43], v[42:43], v[16:17] op_sel_hi:[1,0]
	v_pk_mul_f32 v[40:41], v[40:41], v[16:17] op_sel_hi:[1,0]
	v_pk_mul_f32 v[34:35], v[34:35], v[16:17] op_sel_hi:[1,0]
	v_pk_mul_f32 v[32:33], v[32:33], v[16:17] op_sel_hi:[1,0]
	v_add_f32_e32 v99, v19, v52
	v_cvt_pk_bf16_f32 v52, v64, v65
	v_cvt_pk_bf16_f32 v53, v62, v63
	v_cvt_pk_bf16_f32 v54, v60, v61
	v_cvt_pk_bf16_f32 v55, v58, v59
	s_waitcnt lgkmcnt(0)
	v_fmac_f32_e32 v99, v83, v16
	v_mfma_f32_16x16x32_bf16 v[28:31], v[140:143], v[52:55], v[28:31]
	v_mov_b32_e32 v83, v99
	v_mfma_f32_16x16x32_bf16 v[36:39], v[144:147], v[52:55], v[36:39]
	v_mfma_f32_16x16x32_bf16 v[40:43], v[148:151], v[52:55], v[40:43]
	v_mfma_f32_16x16x32_bf16 v[32:35], v[152:155], v[52:55], v[32:35]
	v_cvt_pk_bf16_f32 v52, v93, v94
	v_cvt_pk_bf16_f32 v53, v95, v96
	v_cvt_pk_bf16_f32 v54, v97, v98
	v_cvt_pk_bf16_f32 v55, v18, v19
	s_waitcnt lgkmcnt(0)
	s_nop 0
	v_mfma_f32_16x16x32_bf16 v[28:31], v[156:159], v[52:55], v[28:31]
	v_mfma_f32_16x16x32_bf16 v[36:39], v[160:163], v[52:55], v[36:39]
	v_mov_b32_e32 v84, v92
	v_mfma_f32_16x16x32_bf16 v[40:43], v[164:167], v[52:55], v[40:43]
	v_mfma_f32_16x16x32_bf16 v[32:35], v[168:171], v[52:55], v[32:35]
